# v17 + gate/up K-loop: LDS-DMA stages rebalanced to 4 per load segment (second B half of each K-tile staged one segment later), waits re-derived as vmcnt 8/6/8/6
# baseline (speedup 1.0000x reference)
; #define PG8_STAGE(bufoff, gbase, voff) do { _Pragma("unroll") for (int _i = 0; _i < 2; ++_i) \
;         __builtin_amdgcn_global_load_lds((const unsigned*)((const char*)(gbase) + (voff)[_i]), (PG8_LAS unsigned*)(lds + (bufoff) + ldsw + _i * 8192), 16, 0, 0); } while (0)
; #define PG8_LDA(dst, b, h) do { _Pragma("unroll") for (int m = 0; m < 4; ++m) _Pragma("unroll") for (int k = 0; k < 2; ++k) dst[m][k] = *(const PG8_LAS bf16x8*)(lds + PG8_SA(b, h) + aoff + m * 2048 + k * 1024); } while (0)
; #define PG8_LDB(dst, b, h) do { _Pragma("unroll") for (int n = 0; n < 2; ++n) _Pragma("unroll") for (int k = 0; k < 2; ++k) dst[n][k] = *(const PG8_LAS bf16x8*)(lds + PG8_SB(b, h) + boff + n * 2048 + k * 1024); } while (0)
; #define PG8_MMA(ai, bj, At, Bt) do { __builtin_amdgcn_s_setprio(1); _Pragma("unroll") for (int m = 0; m < 4; ++m) _Pragma("unroll") for (int n = 0; n < 2; ++n) _Pragma("unroll") for (int k = 0; k < 2; ++k) \
;         acc[ai][bj][m][n] = __builtin_amdgcn_mfma_f32_16x16x32_bf16(Bt[n][k], At[m][k], acc[ai][bj][m][n], 0, 0, 0); __builtin_amdgcn_s_setprio(0); } while (0)
; #define PG8_WAIT_V(n) asm volatile("s_waitcnt vmcnt(" #n ")" ::: "memory")
; #define PG8_WAIT_L(n) asm volatile("s_waitcnt lgkmcnt(" #n ")" ::: "memory")
; #define PG8_BAR __builtin_amdgcn_s_barrier()
; #define PG8_SCHED __builtin_amdgcn_sched_barrier(0)
; template <class Epi, class Sched, bool ALIGN_EPI = false, bool SP2 = false>
; __device__ __forceinline__ void gemm_phase(PG8_LAS unsigned char* lds, const Gemm g, const Sched& S, const Epi& E) {
;     ...
;             PG8_LDB(B0, 0, 0); PG8_LDB(B1, 0, 1); PG8_SCHED; PG8_LDA(At, 0, 0); PG8_STAGE(PG8_SA(1, 1), a1 + hstep, voffA);
;             PG8_WAIT_V(8); PG8_WAIT_L(0); PG8_BAR; PG8_MMA(0, 0, At, B0); PG8_MMA(0, 1, At, B1); PG8_BAR; PG8_SCHED;
;             PG8_LDA(At, 0, 1); PG8_STAGE(PG8_SB(0, 0), b2, voffB); PG8_STAGE(PG8_SB(0, 1), b2 + hstep, voffB); PG8_STAGE(PG8_SA(0, 0), a2, voffA);
;             PG8_WAIT_V(8); PG8_WAIT_L(0); PG8_BAR; PG8_MMA(1, 0, At, B0); PG8_MMA(1, 1, At, B1); PG8_BAR; PG8_SCHED;
.LBB0_492:
	s_ashr_i32 s17, s16, 31
	s_lshl_b64 s[18:19], s[16:17], 19
	s_add_u32 s18, s94, s18
	s_addc_u32 s19, s95, s19
	s_and_b64 s[20:21], s[4:5], exec
	s_cselect_b32 s17, s19, s23
	s_cselect_b32 s46, s18, s22
	s_ashr_i32 s15, s14, 31
	s_lshl_b64 s[20:21], s[14:15], 19
	s_add_u32 s20, s28, s20
	s_addc_u32 s21, s29, s21
	s_and_b64 s[26:27], s[4:5], exec
	s_cselect_b32 s15, s21, s25
	s_cselect_b32 s47, s20, s24
	s_add_u32 s22, s22, 0x40080
	s_addc_u32 s23, s23, 0
	s_add_u32 s48, s24, 0x100
	s_addc_u32 s49, s25, 0
	s_mov_b32 s50, -2
	s_add_u32 s24, s22, 0xfffc0080
	s_addc_u32 s25, s23, -1
	s_add_i32 s51, 0, 0x10000
	s_cmp_eq_u32 s50, 12
	s_cselect_b32 s27, s17, s25
	s_cselect_b32 s26, s46, s24
	v_add_u32_e32 v146, s51, v149
	s_cselect_b32 s25, s15, s49
	s_cselect_b32 s24, s47, s48
	s_add_i32 s54, 0, 0x14000
	ds_read_b128 v[142:145], v146
	ds_read_b128 v[152:155], v146 offset:1024
	ds_read_b128 v[172:175], v146 offset:2048
	ds_read_b128 v[176:179], v146 offset:3072
	v_add_u32_e32 v146, s54, v149
	ds_read_b128 v[180:183], v146
	ds_read_b128 v[184:187], v146 offset:1024
	ds_read_b128 v[188:191], v146 offset:2048
	ds_read_b128 v[192:195], v146 offset:3072
	s_add_i32 m0, s2, 0x1c000
	ds_read_b128 v[196:199], v151
	ds_read_b128 v[214:217], v151 offset:1024
	ds_read_b128 v[218:221], v151 offset:2048
	ds_read_b128 v[222:225], v151 offset:3072
	ds_read_b128 v[226:229], v151 offset:4096
	ds_read_b128 v[230:233], v151 offset:5120
	ds_read_b128 v[234:237], v151 offset:6144
	ds_read_b128 v[238:241], v151 offset:7168
	s_add_u32 s100, s48, 0x3ff80
	s_addc_u32 s101, s49, 0
	global_load_lds_dwordx4 v0, s[100:101]
	s_add_i32 m0, s2, 0x1e000
	s_nop 0
	global_load_lds_dwordx4 v130, s[100:101]
	s_add_i32 m0, s30, 0xc000
	s_nop 0
	global_load_lds_dwordx4 v138, s[22:23]
	s_add_i32 m0, s30, 0xe000
	s_nop 0
	global_load_lds_dwordx4 v140, s[22:23]
	s_waitcnt vmcnt(8)
	s_waitcnt lgkmcnt(0)
	s_barrier
	s_setprio 1
	s_waitcnt lgkmcnt(0)
	v_mfma_f32_16x16x32_bf16 v[126:129], v[142:145], v[196:199], 0
	v_mfma_f32_16x16x32_bf16 v[118:121], v[172:175], v[196:199], 0
	v_mfma_f32_16x16x32_bf16 v[110:113], v[142:145], v[218:221], 0
	v_mfma_f32_16x16x32_bf16 v[102:105], v[172:175], v[218:221], 0
	v_mfma_f32_16x16x32_bf16 v[94:97], v[142:145], v[226:229], 0
	v_mfma_f32_16x16x32_bf16 v[86:89], v[172:175], v[226:229], 0
	v_mfma_f32_16x16x32_bf16 v[78:81], v[142:145], v[234:237], 0
	v_mfma_f32_16x16x32_bf16 v[70:73], v[172:175], v[234:237], 0
	v_mfma_f32_16x16x32_bf16 v[126:129], v[152:155], v[214:217], v[126:129]
	v_mfma_f32_16x16x32_bf16 v[118:121], v[176:179], v[214:217], v[118:121]
	v_mfma_f32_16x16x32_bf16 v[110:113], v[152:155], v[222:225], v[110:113]
	v_mfma_f32_16x16x32_bf16 v[102:105], v[176:179], v[222:225], v[102:105]
	v_mfma_f32_16x16x32_bf16 v[94:97], v[152:155], v[230:233], v[94:97]
	v_mfma_f32_16x16x32_bf16 v[86:89], v[176:179], v[230:233], v[86:89]
	v_mfma_f32_16x16x32_bf16 v[78:81], v[152:155], v[238:241], v[78:81]
	v_mfma_f32_16x16x32_bf16 v[70:73], v[176:179], v[238:241], v[70:73]
	s_setprio 0
	s_setprio 1
	v_mfma_f32_16x16x32_bf16 v[122:125], v[180:183], v[196:199], 0
	v_mfma_f32_16x16x32_bf16 v[114:117], v[188:191], v[196:199], 0
	v_mfma_f32_16x16x32_bf16 v[106:109], v[180:183], v[218:221], 0
	v_mfma_f32_16x16x32_bf16 v[98:101], v[188:191], v[218:221], 0
	v_mfma_f32_16x16x32_bf16 v[90:93], v[180:183], v[226:229], 0
	v_mfma_f32_16x16x32_bf16 v[82:85], v[188:191], v[226:229], 0
	v_mfma_f32_16x16x32_bf16 v[74:77], v[180:183], v[234:237], 0
	v_mfma_f32_16x16x32_bf16 v[66:69], v[188:191], v[234:237], 0
	v_mfma_f32_16x16x32_bf16 v[122:125], v[184:187], v[214:217], v[122:125]
	v_mfma_f32_16x16x32_bf16 v[114:117], v[192:195], v[214:217], v[114:117]
	v_mfma_f32_16x16x32_bf16 v[106:109], v[184:187], v[222:225], v[106:109]
	v_mfma_f32_16x16x32_bf16 v[98:101], v[192:195], v[222:225], v[98:101]
	v_mfma_f32_16x16x32_bf16 v[90:93], v[184:187], v[230:233], v[90:93]
	v_mfma_f32_16x16x32_bf16 v[82:85], v[192:195], v[230:233], v[82:85]
	v_mfma_f32_16x16x32_bf16 v[74:77], v[184:187], v[238:241], v[74:77]
	v_mfma_f32_16x16x32_bf16 v[66:69], v[192:195], v[238:241], v[66:69]
	s_setprio 0
	s_barrier
	s_add_i32 s51, s51, s2
	s_mov_b32 m0, s51
	ds_read_b128 v[196:199], v151 offset:16384
	ds_read_b128 v[214:217], v151 offset:17408
	ds_read_b128 v[218:221], v151 offset:18432
	ds_read_b128 v[222:225], v151 offset:19456
	ds_read_b128 v[226:229], v151 offset:20480
	ds_read_b128 v[230:233], v151 offset:21504
	ds_read_b128 v[234:237], v151 offset:22528
	ds_read_b128 v[238:241], v151 offset:23552
	global_load_lds_dwordx4 v0, s[24:25]
	s_add_i32 m0, s51, 0x2000
	s_nop 0
	global_load_lds_dwordx4 v130, s[24:25]
	s_mov_b32 m0, s30
	s_nop 0
	global_load_lds_dwordx4 v134, s[26:27]
	s_mov_b32 m0, s31
	s_nop 0
	global_load_lds_dwordx4 v132, s[26:27]
	s_waitcnt vmcnt(6)
	s_waitcnt lgkmcnt(0)
	s_barrier
; #define PG8_STAGE(bufoff, gbase, voff) do { _Pragma("unroll") for (int _i = 0; _i < 2; ++_i) \
;         __builtin_amdgcn_global_load_lds((const unsigned*)((const char*)(gbase) + (voff)[_i]), (PG8_LAS unsigned*)(lds + (bufoff) + ldsw + _i * 8192), 16, 0, 0); } while (0)
; #define PG8_LDA(dst, b, h) do { _Pragma("unroll") for (int m = 0; m < 4; ++m) _Pragma("unroll") for (int k = 0; k < 2; ++k) dst[m][k] = *(const PG8_LAS bf16x8*)(lds + PG8_SA(b, h) + aoff + m * 2048 + k * 1024); } while (0)
; #define PG8_LDB(dst, b, h) do { _Pragma("unroll") for (int n = 0; n < 2; ++n) _Pragma("unroll") for (int k = 0; k < 2; ++k) dst[n][k] = *(const PG8_LAS bf16x8*)(lds + PG8_SB(b, h) + boff + n * 2048 + k * 1024); } while (0)
; #define PG8_MMA(ai, bj, At, Bt) do { __builtin_amdgcn_s_setprio(1); _Pragma("unroll") for (int m = 0; m < 4; ++m) _Pragma("unroll") for (int n = 0; n < 2; ++n) _Pragma("unroll") for (int k = 0; k < 2; ++k) \
;         acc[ai][bj][m][n] = __builtin_amdgcn_mfma_f32_16x16x32_bf16(Bt[n][k], At[m][k], acc[ai][bj][m][n], 0, 0, 0); __builtin_amdgcn_s_setprio(0); } while (0)
; #define PG8_WAIT_V(n) asm volatile("s_waitcnt vmcnt(" #n ")" ::: "memory")
; #define PG8_WAIT_L(n) asm volatile("s_waitcnt lgkmcnt(" #n ")" ::: "memory")
; #define PG8_BAR __builtin_amdgcn_s_barrier()
; #define PG8_SCHED __builtin_amdgcn_sched_barrier(0)
; template <class Epi, class Sched, bool ALIGN_EPI = false, bool SP2 = false>
; __device__ __forceinline__ void gemm_phase(PG8_LAS unsigned char* lds, const Gemm g, const Sched& S, const Epi& E) {
;     ...
;             PG8_WAIT_V(8); PG8_WAIT_L(0); PG8_BAR; PG8_MMA(1, 0, At, B0); PG8_MMA(1, 1, At, B1); PG8_BAR; PG8_SCHED;
;             PG8_LDB(B0, 1, 0); PG8_LDB(B1, 1, 1); PG8_SCHED; PG8_LDA(At, 1, 0); PG8_STAGE(PG8_SA(0, 1), a2 + hstep, voffA);
;             PG8_WAIT_V(8); PG8_WAIT_L(0); PG8_BAR; PG8_MMA(0, 0, At, B0); PG8_MMA(0, 1, At, B1); PG8_BAR; PG8_SCHED;
;             PG8_LDA(At, 1, 1); PG8_STAGE(PG8_SB(1, 0), b3, voffB); PG8_STAGE(PG8_SB(1, 1), b3 + hstep, voffB); PG8_STAGE(PG8_SA(1, 0), a3, voffA);
	s_setprio 1
	s_waitcnt lgkmcnt(0)
	v_mfma_f32_16x16x32_bf16 v[62:65], v[142:145], v[196:199], 0
	v_mfma_f32_16x16x32_bf16 v[54:57], v[172:175], v[196:199], 0
	v_mfma_f32_16x16x32_bf16 v[46:49], v[142:145], v[218:221], 0
	v_mfma_f32_16x16x32_bf16 v[38:41], v[172:175], v[218:221], 0
	v_mfma_f32_16x16x32_bf16 v[30:33], v[142:145], v[226:229], 0
	v_mfma_f32_16x16x32_bf16 v[22:25], v[172:175], v[226:229], 0
	v_mfma_f32_16x16x32_bf16 v[14:17], v[142:145], v[234:237], 0
	v_mfma_f32_16x16x32_bf16 v[6:9], v[172:175], v[234:237], 0
	v_mfma_f32_16x16x32_bf16 v[62:65], v[152:155], v[214:217], v[62:65]
	v_mfma_f32_16x16x32_bf16 v[54:57], v[176:179], v[214:217], v[54:57]
	v_mfma_f32_16x16x32_bf16 v[46:49], v[152:155], v[222:225], v[46:49]
	v_mfma_f32_16x16x32_bf16 v[38:41], v[176:179], v[222:225], v[38:41]
	v_mfma_f32_16x16x32_bf16 v[30:33], v[152:155], v[230:233], v[30:33]
	v_mfma_f32_16x16x32_bf16 v[22:25], v[176:179], v[230:233], v[22:25]
	v_mfma_f32_16x16x32_bf16 v[14:17], v[152:155], v[238:241], v[14:17]
	v_mfma_f32_16x16x32_bf16 v[6:9], v[176:179], v[238:241], v[6:9]
	s_setprio 0
	s_setprio 1
	v_mfma_f32_16x16x32_bf16 v[58:61], v[180:183], v[196:199], 0
	v_mfma_f32_16x16x32_bf16 v[50:53], v[188:191], v[196:199], 0
	v_mfma_f32_16x16x32_bf16 v[42:45], v[180:183], v[218:221], 0
	v_mfma_f32_16x16x32_bf16 v[34:37], v[188:191], v[218:221], 0
	v_mfma_f32_16x16x32_bf16 v[26:29], v[180:183], v[226:229], 0
	v_mfma_f32_16x16x32_bf16 v[18:21], v[188:191], v[226:229], 0
	v_mfma_f32_16x16x32_bf16 v[10:13], v[180:183], v[234:237], 0
	v_mfma_f32_16x16x32_bf16 v[2:5], v[188:191], v[234:237], 0
	v_mfma_f32_16x16x32_bf16 v[58:61], v[184:187], v[214:217], v[58:61]
	v_mfma_f32_16x16x32_bf16 v[50:53], v[192:195], v[214:217], v[50:53]
	v_mfma_f32_16x16x32_bf16 v[42:45], v[184:187], v[222:225], v[42:45]
	v_mfma_f32_16x16x32_bf16 v[34:37], v[192:195], v[222:225], v[34:37]
	v_mfma_f32_16x16x32_bf16 v[26:29], v[184:187], v[230:233], v[26:29]
	v_mfma_f32_16x16x32_bf16 v[18:21], v[192:195], v[230:233], v[18:21]
	v_mfma_f32_16x16x32_bf16 v[10:13], v[184:187], v[238:241], v[10:13]
	v_mfma_f32_16x16x32_bf16 v[2:5], v[192:195], v[238:241], v[2:5]
	s_setprio 0
	s_barrier
	s_add_i32 s51, 0, 0x18000
	v_add_u32_e32 v158, s51, v149
	s_add_i32 s52, 0, 0x1c000
	ds_read_b128 v[142:145], v158
	ds_read_b128 v[152:155], v158 offset:1024
	ds_read_b128 v[172:175], v158 offset:2048
	ds_read_b128 v[176:179], v158 offset:3072
	v_add_u32_e32 v158, s52, v149
	ds_read_b128 v[180:183], v158
	ds_read_b128 v[184:187], v158 offset:1024
	ds_read_b128 v[188:191], v158 offset:2048
	ds_read_b128 v[192:195], v158 offset:3072
	s_add_u32 s26, s26, 0x40000
	s_addc_u32 s27, s27, 0
	s_add_i32 m0, s2, 0x14000
	ds_read_b128 v[196:199], v151 offset:32768
	ds_read_b128 v[214:217], v151 offset:33792
	ds_read_b128 v[218:221], v151 offset:34816
	ds_read_b128 v[222:225], v151 offset:35840
	ds_read_b128 v[226:229], v151 offset:36864
	ds_read_b128 v[230:233], v151 offset:37888
	ds_read_b128 v[234:237], v151 offset:38912
	ds_read_b128 v[238:241], v151 offset:39936
	s_add_u32 s100, s24, 0x40000
	s_addc_u32 s101, s25, 0
	global_load_lds_dwordx4 v0, s[100:101]
	s_add_i32 m0, s2, 0x16000
	s_nop 0
	global_load_lds_dwordx4 v130, s[100:101]
	s_mov_b32 m0, s34
	s_nop 0
	global_load_lds_dwordx4 v134, s[26:27]
	s_mov_b32 m0, s35
	s_nop 0
	global_load_lds_dwordx4 v132, s[26:27]
	s_waitcnt vmcnt(8)
	s_waitcnt lgkmcnt(0)
	s_barrier
	s_setprio 1
	s_waitcnt lgkmcnt(0)
	v_mfma_f32_16x16x32_bf16 v[126:129], v[142:145], v[196:199], v[126:129]
	v_mfma_f32_16x16x32_bf16 v[118:121], v[172:175], v[196:199], v[118:121]
	v_mfma_f32_16x16x32_bf16 v[110:113], v[142:145], v[218:221], v[110:113]
	v_mfma_f32_16x16x32_bf16 v[102:105], v[172:175], v[218:221], v[102:105]
	v_mfma_f32_16x16x32_bf16 v[94:97], v[142:145], v[226:229], v[94:97]
	v_mfma_f32_16x16x32_bf16 v[86:89], v[172:175], v[226:229], v[86:89]
	v_mfma_f32_16x16x32_bf16 v[78:81], v[142:145], v[234:237], v[78:81]
	v_mfma_f32_16x16x32_bf16 v[70:73], v[172:175], v[234:237], v[70:73]
	v_mfma_f32_16x16x32_bf16 v[126:129], v[152:155], v[214:217], v[126:129]
	v_mfma_f32_16x16x32_bf16 v[118:121], v[176:179], v[214:217], v[118:121]
	v_mfma_f32_16x16x32_bf16 v[110:113], v[152:155], v[222:225], v[110:113]
	v_mfma_f32_16x16x32_bf16 v[102:105], v[176:179], v[222:225], v[102:105]
	v_mfma_f32_16x16x32_bf16 v[94:97], v[152:155], v[230:233], v[94:97]
	v_mfma_f32_16x16x32_bf16 v[86:89], v[176:179], v[230:233], v[86:89]
	v_mfma_f32_16x16x32_bf16 v[78:81], v[152:155], v[238:241], v[78:81]
	v_mfma_f32_16x16x32_bf16 v[70:73], v[176:179], v[238:241], v[70:73]
	s_setprio 0
	s_setprio 1
	v_mfma_f32_16x16x32_bf16 v[122:125], v[180:183], v[196:199], v[122:125]
	v_mfma_f32_16x16x32_bf16 v[114:117], v[188:191], v[196:199], v[114:117]
	v_mfma_f32_16x16x32_bf16 v[106:109], v[180:183], v[218:221], v[106:109]
	v_mfma_f32_16x16x32_bf16 v[98:101], v[188:191], v[218:221], v[98:101]
	v_mfma_f32_16x16x32_bf16 v[90:93], v[180:183], v[226:229], v[90:93]
	v_mfma_f32_16x16x32_bf16 v[82:85], v[188:191], v[226:229], v[82:85]
	v_mfma_f32_16x16x32_bf16 v[74:77], v[180:183], v[234:237], v[74:77]
	v_mfma_f32_16x16x32_bf16 v[66:69], v[188:191], v[234:237], v[66:69]
	v_mfma_f32_16x16x32_bf16 v[122:125], v[184:187], v[214:217], v[122:125]
	v_mfma_f32_16x16x32_bf16 v[114:117], v[192:195], v[214:217], v[114:117]
	v_mfma_f32_16x16x32_bf16 v[106:109], v[184:187], v[222:225], v[106:109]
	v_mfma_f32_16x16x32_bf16 v[98:101], v[192:195], v[222:225], v[98:101]
	v_mfma_f32_16x16x32_bf16 v[90:93], v[184:187], v[230:233], v[90:93]
	v_mfma_f32_16x16x32_bf16 v[82:85], v[192:195], v[230:233], v[82:85]
	v_mfma_f32_16x16x32_bf16 v[74:77], v[184:187], v[238:241], v[74:77]
	v_mfma_f32_16x16x32_bf16 v[66:69], v[192:195], v[238:241], v[66:69]
	s_setprio 0
	s_barrier
; #define PG8_STAGE(bufoff, gbase, voff) do { _Pragma("unroll") for (int _i = 0; _i < 2; ++_i) \
;         __builtin_amdgcn_global_load_lds((const unsigned*)((const char*)(gbase) + (voff)[_i]), (PG8_LAS unsigned*)(lds + (bufoff) + ldsw + _i * 8192), 16, 0, 0); } while (0)
; #define PG8_LDA(dst, b, h) do { _Pragma("unroll") for (int m = 0; m < 4; ++m) _Pragma("unroll") for (int k = 0; k < 2; ++k) dst[m][k] = *(const PG8_LAS bf16x8*)(lds + PG8_SA(b, h) + aoff + m * 2048 + k * 1024); } while (0)
; #define PG8_LDB(dst, b, h) do { _Pragma("unroll") for (int n = 0; n < 2; ++n) _Pragma("unroll") for (int k = 0; k < 2; ++k) dst[n][k] = *(const PG8_LAS bf16x8*)(lds + PG8_SB(b, h) + boff + n * 2048 + k * 1024); } while (0)
; #define PG8_MMA(ai, bj, At, Bt) do { __builtin_amdgcn_s_setprio(1); _Pragma("unroll") for (int m = 0; m < 4; ++m) _Pragma("unroll") for (int n = 0; n < 2; ++n) _Pragma("unroll") for (int k = 0; k < 2; ++k) \
;         acc[ai][bj][m][n] = __builtin_amdgcn_mfma_f32_16x16x32_bf16(Bt[n][k], At[m][k], acc[ai][bj][m][n], 0, 0, 0); __builtin_amdgcn_s_setprio(0); } while (0)
; #define PG8_WAIT_V(n) asm volatile("s_waitcnt vmcnt(" #n ")" ::: "memory")
; #define PG8_BAR __builtin_amdgcn_s_barrier()
; template <class Epi, class Sched, bool ALIGN_EPI = false, bool SP2 = false>
; __device__ __forceinline__ void gemm_phase(PG8_LAS unsigned char* lds, const Gemm g, const Sched& S, const Epi& E) {
;     ...
;         for (int t = 0; t < nt; t += 2) {
;             const bool last = (t == nt - 2);
;             const char* a1 = cA + (size_t)(t + 1) * kstep;
;             const char* a2 = last ? nA : cA + (size_t)(t + 2) * kstep; const char* b2 = last ? nB : cB + (size_t)(t + 2) * kstep;
;             const char* a3 = a2 + kstep; const char* b3 = b2 + kstep;
;             if (last && has_next) S.a_ready(nxt);
;             if constexpr (SP2) {
;             PG8_LDB(B0, 0, 0); PG8_LDB(B1, 0, 1); PG8_SCHED; PG8_LDA(At, 0, 0); PG8_STAGE(PG8_SA(1, 1), a1 + hstep, voffA);
;             PG8_WAIT_V(8); PG8_WAIT_L(0); PG8_BAR; PG8_MMA(0, 0, At, B0); PG8_MMA(0, 1, At, B1); PG8_BAR; PG8_SCHED;
;     ...
;             PG8_LDA(At, 1, 1); PG8_STAGE(PG8_SB(1, 0), b3, voffB); PG8_STAGE(PG8_SB(1, 1), b3 + hstep, voffB); PG8_STAGE(PG8_SA(1, 0), a3, voffA);
;             PG8_WAIT_V(8); PG8_WAIT_L(0); PG8_BAR; PG8_MMA(1, 0, At, B0); PG8_MMA(1, 1, At, B1); PG8_BAR; PG8_SCHED;
	s_add_u32 s98, s26, 0xfffc0080
	s_addc_u32 s99, s27, -1
	s_add_i32 s26, s51, s2
	s_add_u32 s100, s24, 0x80
	s_addc_u32 s101, s25, 0
	s_mov_b32 m0, s26
	ds_read_b128 v[196:199], v151 offset:49152
	ds_read_b128 v[214:217], v151 offset:50176
	ds_read_b128 v[218:221], v151 offset:51200
	ds_read_b128 v[222:225], v151 offset:52224
	ds_read_b128 v[226:229], v151 offset:53248
	ds_read_b128 v[230:233], v151 offset:54272
	ds_read_b128 v[234:237], v151 offset:55296
	ds_read_b128 v[238:241], v151 offset:56320
	global_load_lds_dwordx4 v0, s[100:101]
	s_add_i32 m0, s26, 0x2000
	s_nop 0
	global_load_lds_dwordx4 v130, s[100:101]
	s_mov_b32 m0, s37
	s_nop 0
	global_load_lds_dwordx4 v134, s[98:99]
	s_mov_b32 m0, s38
	s_nop 0
	global_load_lds_dwordx4 v132, s[98:99]
	s_waitcnt vmcnt(6)
	s_waitcnt lgkmcnt(0)
	s_barrier
	s_setprio 1
	s_waitcnt lgkmcnt(0)
	v_mfma_f32_16x16x32_bf16 v[62:65], v[142:145], v[196:199], v[62:65]
	v_mfma_f32_16x16x32_bf16 v[54:57], v[172:175], v[196:199], v[54:57]
	v_mfma_f32_16x16x32_bf16 v[46:49], v[142:145], v[218:221], v[46:49]
	v_mfma_f32_16x16x32_bf16 v[38:41], v[172:175], v[218:221], v[38:41]
	v_mfma_f32_16x16x32_bf16 v[30:33], v[142:145], v[226:229], v[30:33]
	v_mfma_f32_16x16x32_bf16 v[22:25], v[172:175], v[226:229], v[22:25]
	v_mfma_f32_16x16x32_bf16 v[14:17], v[142:145], v[234:237], v[14:17]
	v_mfma_f32_16x16x32_bf16 v[6:9], v[172:175], v[234:237], v[6:9]
	v_mfma_f32_16x16x32_bf16 v[62:65], v[152:155], v[214:217], v[62:65]
	v_mfma_f32_16x16x32_bf16 v[54:57], v[176:179], v[214:217], v[54:57]
	v_mfma_f32_16x16x32_bf16 v[46:49], v[152:155], v[222:225], v[46:49]
	v_mfma_f32_16x16x32_bf16 v[38:41], v[176:179], v[222:225], v[38:41]
	v_mfma_f32_16x16x32_bf16 v[30:33], v[152:155], v[230:233], v[30:33]
	v_mfma_f32_16x16x32_bf16 v[22:25], v[176:179], v[230:233], v[22:25]
	v_mfma_f32_16x16x32_bf16 v[14:17], v[152:155], v[238:241], v[14:17]
	v_mfma_f32_16x16x32_bf16 v[6:9], v[176:179], v[238:241], v[6:9]
	s_setprio 0
	s_setprio 1
	v_mfma_f32_16x16x32_bf16 v[58:61], v[180:183], v[196:199], v[58:61]
	v_mfma_f32_16x16x32_bf16 v[50:53], v[188:191], v[196:199], v[50:53]
	v_mfma_f32_16x16x32_bf16 v[42:45], v[180:183], v[218:221], v[42:45]
	v_mfma_f32_16x16x32_bf16 v[34:37], v[188:191], v[218:221], v[34:37]
	v_mfma_f32_16x16x32_bf16 v[26:29], v[180:183], v[226:229], v[26:29]
	v_mfma_f32_16x16x32_bf16 v[18:21], v[188:191], v[226:229], v[18:21]
	v_mfma_f32_16x16x32_bf16 v[10:13], v[180:183], v[234:237], v[10:13]
	v_mfma_f32_16x16x32_bf16 v[2:5], v[188:191], v[234:237], v[2:5]
	v_mfma_f32_16x16x32_bf16 v[58:61], v[184:187], v[214:217], v[58:61]
	v_mfma_f32_16x16x32_bf16 v[50:53], v[192:195], v[214:217], v[50:53]
	v_mfma_f32_16x16x32_bf16 v[42:45], v[184:187], v[222:225], v[42:45]
	v_mfma_f32_16x16x32_bf16 v[34:37], v[192:195], v[222:225], v[34:37]
	v_mfma_f32_16x16x32_bf16 v[26:29], v[184:187], v[230:233], v[26:29]
	v_mfma_f32_16x16x32_bf16 v[18:21], v[192:195], v[230:233], v[18:21]
	v_mfma_f32_16x16x32_bf16 v[10:13], v[184:187], v[238:241], v[10:13]
	v_mfma_f32_16x16x32_bf16 v[2:5], v[192:195], v[238:241], v[2:5]
	s_setprio 0
	s_barrier
	s_add_i32 s50, s50, 2
	s_add_u32 s22, s22, 0x100
	s_addc_u32 s23, s23, 0
	s_add_u32 s48, s48, 0x100
	s_addc_u32 s49, s49, 0
.LBB0_493:
	s_add_u32 s24, s22, 0xfffc0080
	s_addc_u32 s25, s23, -1
	s_add_i32 s51, 0, 0x10000
	s_cmp_eq_u32 s50, 12
	s_cselect_b32 s27, s17, s25
	s_cselect_b32 s26, s46, s24
	v_add_u32_e32 v146, s51, v149
	s_cselect_b32 s25, s15, s49
	s_cselect_b32 s24, s47, s48
	s_add_i32 s54, 0, 0x14000
	ds_read_b128 v[142:145], v146
	ds_read_b128 v[152:155], v146 offset:1024
	ds_read_b128 v[172:175], v146 offset:2048
	ds_read_b128 v[176:179], v146 offset:3072
	v_add_u32_e32 v146, s54, v149
	ds_read_b128 v[180:183], v146
	ds_read_b128 v[184:187], v146 offset:1024
	ds_read_b128 v[188:191], v146 offset:2048
	ds_read_b128 v[192:195], v146 offset:3072
	s_add_i32 m0, s2, 0x1c000
	ds_read_b128 v[196:199], v151
	ds_read_b128 v[214:217], v151 offset:1024
	ds_read_b128 v[218:221], v151 offset:2048
	ds_read_b128 v[222:225], v151 offset:3072
	ds_read_b128 v[226:229], v151 offset:4096
	ds_read_b128 v[230:233], v151 offset:5120
	ds_read_b128 v[234:237], v151 offset:6144
	ds_read_b128 v[238:241], v151 offset:7168
	s_add_u32 s100, s48, 0x3ff80
	s_addc_u32 s101, s49, 0
	global_load_lds_dwordx4 v0, s[100:101]
	s_add_i32 m0, s2, 0x1e000
	s_nop 0
	global_load_lds_dwordx4 v130, s[100:101]
	s_add_i32 m0, s30, 0xc000
	s_nop 0
	global_load_lds_dwordx4 v138, s[22:23]
	s_add_i32 m0, s30, 0xe000
	s_nop 0
	global_load_lds_dwordx4 v140, s[22:23]
	s_waitcnt vmcnt(8)
	s_waitcnt lgkmcnt(0)
	s_barrier
; #define PG8_STAGE(bufoff, gbase, voff) do { _Pragma("unroll") for (int _i = 0; _i < 2; ++_i) \
;         __builtin_amdgcn_global_load_lds((const unsigned*)((const char*)(gbase) + (voff)[_i]), (PG8_LAS unsigned*)(lds + (bufoff) + ldsw + _i * 8192), 16, 0, 0); } while (0)
; #define PG8_LDA(dst, b, h) do { _Pragma("unroll") for (int m = 0; m < 4; ++m) _Pragma("unroll") for (int k = 0; k < 2; ++k) dst[m][k] = *(const PG8_LAS bf16x8*)(lds + PG8_SA(b, h) + aoff + m * 2048 + k * 1024); } while (0)
; #define PG8_MMA(ai, bj, At, Bt) do { __builtin_amdgcn_s_setprio(1); _Pragma("unroll") for (int m = 0; m < 4; ++m) _Pragma("unroll") for (int n = 0; n < 2; ++n) _Pragma("unroll") for (int k = 0; k < 2; ++k) \
;         acc[ai][bj][m][n] = __builtin_amdgcn_mfma_f32_16x16x32_bf16(Bt[n][k], At[m][k], acc[ai][bj][m][n], 0, 0, 0); __builtin_amdgcn_s_setprio(0); } while (0)
; #define PG8_WAIT_V(n) asm volatile("s_waitcnt vmcnt(" #n ")" ::: "memory")
; #define PG8_WAIT_L(n) asm volatile("s_waitcnt lgkmcnt(" #n ")" ::: "memory")
; #define PG8_BAR __builtin_amdgcn_s_barrier()
; #define PG8_SCHED __builtin_amdgcn_sched_barrier(0)
; template <class Epi, class Sched, bool ALIGN_EPI = false, bool SP2 = false>
; __device__ __forceinline__ void gemm_phase(PG8_LAS unsigned char* lds, const Gemm g, const Sched& S, const Epi& E) {
;     ...
;             PG8_WAIT_V(8); PG8_WAIT_L(0); PG8_BAR; PG8_MMA(0, 0, At, B0); PG8_MMA(0, 1, At, B1); PG8_BAR; PG8_SCHED;
;             PG8_LDA(At, 0, 1); PG8_STAGE(PG8_SB(0, 0), b2, voffB); PG8_STAGE(PG8_SB(0, 1), b2 + hstep, voffB); PG8_STAGE(PG8_SA(0, 0), a2, voffA);
;             PG8_WAIT_V(8); PG8_WAIT_L(0); PG8_BAR; PG8_MMA(1, 0, At, B0); PG8_MMA(1, 1, At, B1); PG8_BAR; PG8_SCHED;
	s_setprio 1
	s_waitcnt lgkmcnt(0)
	v_mfma_f32_16x16x32_bf16 v[126:129], v[142:145], v[196:199], v[126:129]
	v_mfma_f32_16x16x32_bf16 v[118:121], v[172:175], v[196:199], v[118:121]
	v_mfma_f32_16x16x32_bf16 v[110:113], v[142:145], v[218:221], v[110:113]
	v_mfma_f32_16x16x32_bf16 v[102:105], v[172:175], v[218:221], v[102:105]
	v_mfma_f32_16x16x32_bf16 v[94:97], v[142:145], v[226:229], v[94:97]
	v_mfma_f32_16x16x32_bf16 v[86:89], v[172:175], v[226:229], v[86:89]
	v_mfma_f32_16x16x32_bf16 v[78:81], v[142:145], v[234:237], v[78:81]
	v_mfma_f32_16x16x32_bf16 v[70:73], v[172:175], v[234:237], v[70:73]
	v_mfma_f32_16x16x32_bf16 v[126:129], v[152:155], v[214:217], v[126:129]
	v_mfma_f32_16x16x32_bf16 v[118:121], v[176:179], v[214:217], v[118:121]
	v_mfma_f32_16x16x32_bf16 v[110:113], v[152:155], v[222:225], v[110:113]
	v_mfma_f32_16x16x32_bf16 v[102:105], v[176:179], v[222:225], v[102:105]
	v_mfma_f32_16x16x32_bf16 v[94:97], v[152:155], v[230:233], v[94:97]
	v_mfma_f32_16x16x32_bf16 v[86:89], v[176:179], v[230:233], v[86:89]
	v_mfma_f32_16x16x32_bf16 v[78:81], v[152:155], v[238:241], v[78:81]
	v_mfma_f32_16x16x32_bf16 v[70:73], v[176:179], v[238:241], v[70:73]
	s_setprio 0
	s_setprio 1
	v_mfma_f32_16x16x32_bf16 v[122:125], v[180:183], v[196:199], v[122:125]
	v_mfma_f32_16x16x32_bf16 v[114:117], v[188:191], v[196:199], v[114:117]
	v_mfma_f32_16x16x32_bf16 v[106:109], v[180:183], v[218:221], v[106:109]
	v_mfma_f32_16x16x32_bf16 v[98:101], v[188:191], v[218:221], v[98:101]
	v_mfma_f32_16x16x32_bf16 v[90:93], v[180:183], v[226:229], v[90:93]
	v_mfma_f32_16x16x32_bf16 v[82:85], v[188:191], v[226:229], v[82:85]
	v_mfma_f32_16x16x32_bf16 v[74:77], v[180:183], v[234:237], v[74:77]
	v_mfma_f32_16x16x32_bf16 v[66:69], v[188:191], v[234:237], v[66:69]
	v_mfma_f32_16x16x32_bf16 v[122:125], v[184:187], v[214:217], v[122:125]
	v_mfma_f32_16x16x32_bf16 v[114:117], v[192:195], v[214:217], v[114:117]
	v_mfma_f32_16x16x32_bf16 v[106:109], v[184:187], v[222:225], v[106:109]
	v_mfma_f32_16x16x32_bf16 v[98:101], v[192:195], v[222:225], v[98:101]
	v_mfma_f32_16x16x32_bf16 v[90:93], v[184:187], v[230:233], v[90:93]
	v_mfma_f32_16x16x32_bf16 v[82:85], v[192:195], v[230:233], v[82:85]
	v_mfma_f32_16x16x32_bf16 v[74:77], v[184:187], v[238:241], v[74:77]
	v_mfma_f32_16x16x32_bf16 v[66:69], v[192:195], v[238:241], v[66:69]
	s_setprio 0
	s_barrier
	s_add_i32 s51, s51, s2
	s_mov_b32 m0, s51
	ds_read_b128 v[196:199], v151 offset:16384
	ds_read_b128 v[214:217], v151 offset:17408
	ds_read_b128 v[218:221], v151 offset:18432
	ds_read_b128 v[222:225], v151 offset:19456
	ds_read_b128 v[226:229], v151 offset:20480
	ds_read_b128 v[230:233], v151 offset:21504
	ds_read_b128 v[234:237], v151 offset:22528
	ds_read_b128 v[238:241], v151 offset:23552
	global_load_lds_dwordx4 v0, s[24:25]
	s_add_i32 m0, s51, 0x2000
	s_nop 0
	global_load_lds_dwordx4 v130, s[24:25]
	s_mov_b32 m0, s30
	s_nop 0
	global_load_lds_dwordx4 v134, s[26:27]
	s_mov_b32 m0, s31
	s_nop 0
	global_load_lds_dwordx4 v132, s[26:27]
	s_waitcnt vmcnt(6)
	s_waitcnt lgkmcnt(0)
	s_barrier
	s_setprio 1
	s_waitcnt lgkmcnt(0)
	v_mfma_f32_16x16x32_bf16 v[62:65], v[142:145], v[196:199], v[62:65]
	v_mfma_f32_16x16x32_bf16 v[54:57], v[172:175], v[196:199], v[54:57]
	v_mfma_f32_16x16x32_bf16 v[46:49], v[142:145], v[218:221], v[46:49]
	v_mfma_f32_16x16x32_bf16 v[38:41], v[172:175], v[218:221], v[38:41]
	v_mfma_f32_16x16x32_bf16 v[30:33], v[142:145], v[226:229], v[30:33]
	v_mfma_f32_16x16x32_bf16 v[22:25], v[172:175], v[226:229], v[22:25]
	v_mfma_f32_16x16x32_bf16 v[14:17], v[142:145], v[234:237], v[14:17]
	v_mfma_f32_16x16x32_bf16 v[6:9], v[172:175], v[234:237], v[6:9]
	v_mfma_f32_16x16x32_bf16 v[62:65], v[152:155], v[214:217], v[62:65]
	v_mfma_f32_16x16x32_bf16 v[54:57], v[176:179], v[214:217], v[54:57]
	v_mfma_f32_16x16x32_bf16 v[46:49], v[152:155], v[222:225], v[46:49]
	v_mfma_f32_16x16x32_bf16 v[38:41], v[176:179], v[222:225], v[38:41]
	v_mfma_f32_16x16x32_bf16 v[30:33], v[152:155], v[230:233], v[30:33]
	v_mfma_f32_16x16x32_bf16 v[22:25], v[176:179], v[230:233], v[22:25]
	v_mfma_f32_16x16x32_bf16 v[14:17], v[152:155], v[238:241], v[14:17]
	v_mfma_f32_16x16x32_bf16 v[6:9], v[176:179], v[238:241], v[6:9]
	s_setprio 0
	s_setprio 1
	v_mfma_f32_16x16x32_bf16 v[58:61], v[180:183], v[196:199], v[58:61]
	v_mfma_f32_16x16x32_bf16 v[50:53], v[188:191], v[196:199], v[50:53]
	v_mfma_f32_16x16x32_bf16 v[42:45], v[180:183], v[218:221], v[42:45]
	v_mfma_f32_16x16x32_bf16 v[34:37], v[188:191], v[218:221], v[34:37]
	v_mfma_f32_16x16x32_bf16 v[26:29], v[180:183], v[226:229], v[26:29]
	v_mfma_f32_16x16x32_bf16 v[18:21], v[188:191], v[226:229], v[18:21]
	v_mfma_f32_16x16x32_bf16 v[10:13], v[180:183], v[234:237], v[10:13]
	v_mfma_f32_16x16x32_bf16 v[2:5], v[188:191], v[234:237], v[2:5]
	v_mfma_f32_16x16x32_bf16 v[58:61], v[184:187], v[214:217], v[58:61]
	v_mfma_f32_16x16x32_bf16 v[50:53], v[192:195], v[214:217], v[50:53]
	v_mfma_f32_16x16x32_bf16 v[42:45], v[184:187], v[222:225], v[42:45]
	v_mfma_f32_16x16x32_bf16 v[34:37], v[192:195], v[222:225], v[34:37]
	v_mfma_f32_16x16x32_bf16 v[26:29], v[184:187], v[230:233], v[26:29]
	v_mfma_f32_16x16x32_bf16 v[18:21], v[192:195], v[230:233], v[18:21]
	v_mfma_f32_16x16x32_bf16 v[10:13], v[184:187], v[238:241], v[10:13]
	v_mfma_f32_16x16x32_bf16 v[2:5], v[192:195], v[238:241], v[2:5]
	s_setprio 0
	s_barrier
; #define PG8_STAGE(bufoff, gbase, voff) do { _Pragma("unroll") for (int _i = 0; _i < 2; ++_i) \
;         __builtin_amdgcn_global_load_lds((const unsigned*)((const char*)(gbase) + (voff)[_i]), (PG8_LAS unsigned*)(lds + (bufoff) + ldsw + _i * 8192), 16, 0, 0); } while (0)
; #define PG8_LDA(dst, b, h) do { _Pragma("unroll") for (int m = 0; m < 4; ++m) _Pragma("unroll") for (int k = 0; k < 2; ++k) dst[m][k] = *(const PG8_LAS bf16x8*)(lds + PG8_SA(b, h) + aoff + m * 2048 + k * 1024); } while (0)
; #define PG8_LDB(dst, b, h) do { _Pragma("unroll") for (int n = 0; n < 2; ++n) _Pragma("unroll") for (int k = 0; k < 2; ++k) dst[n][k] = *(const PG8_LAS bf16x8*)(lds + PG8_SB(b, h) + boff + n * 2048 + k * 1024); } while (0)
; #define PG8_MMA(ai, bj, At, Bt) do { __builtin_amdgcn_s_setprio(1); _Pragma("unroll") for (int m = 0; m < 4; ++m) _Pragma("unroll") for (int n = 0; n < 2; ++n) _Pragma("unroll") for (int k = 0; k < 2; ++k) \
;         acc[ai][bj][m][n] = __builtin_amdgcn_mfma_f32_16x16x32_bf16(Bt[n][k], At[m][k], acc[ai][bj][m][n], 0, 0, 0); __builtin_amdgcn_s_setprio(0); } while (0)
; #define PG8_WAIT_V(n) asm volatile("s_waitcnt vmcnt(" #n ")" ::: "memory")
; #define PG8_WAIT_L(n) asm volatile("s_waitcnt lgkmcnt(" #n ")" ::: "memory")
; #define PG8_BAR __builtin_amdgcn_s_barrier()
; #define PG8_SCHED __builtin_amdgcn_sched_barrier(0)
; template <class Epi, class Sched, bool ALIGN_EPI = false, bool SP2 = false>
; __device__ __forceinline__ void gemm_phase(PG8_LAS unsigned char* lds, const Gemm g, const Sched& S, const Epi& E) {
;     ...
;             PG8_LDB(B0, 1, 0); PG8_LDB(B1, 1, 1); PG8_SCHED; PG8_LDA(At, 1, 0); PG8_STAGE(PG8_SA(0, 1), a2 + hstep, voffA);
;             PG8_WAIT_V(8); PG8_WAIT_L(0); PG8_BAR; PG8_MMA(0, 0, At, B0); PG8_MMA(0, 1, At, B1); PG8_BAR; PG8_SCHED;
;             PG8_LDA(At, 1, 1); PG8_STAGE(PG8_SB(1, 0), b3, voffB); PG8_STAGE(PG8_SB(1, 1), b3 + hstep, voffB); PG8_STAGE(PG8_SA(1, 0), a3, voffA);
	s_add_i32 s51, 0, 0x18000
	v_add_u32_e32 v158, s51, v149
	s_add_i32 s52, 0, 0x1c000
	ds_read_b128 v[142:145], v158
	ds_read_b128 v[152:155], v158 offset:1024
	ds_read_b128 v[172:175], v158 offset:2048
	ds_read_b128 v[176:179], v158 offset:3072
	v_add_u32_e32 v158, s52, v149
	ds_read_b128 v[180:183], v158
	ds_read_b128 v[184:187], v158 offset:1024
	ds_read_b128 v[188:191], v158 offset:2048
	ds_read_b128 v[192:195], v158 offset:3072
	s_add_u32 s26, s26, 0x40000
	s_addc_u32 s27, s27, 0
	s_add_i32 m0, s2, 0x14000
	ds_read_b128 v[196:199], v151 offset:32768
	ds_read_b128 v[214:217], v151 offset:33792
	ds_read_b128 v[218:221], v151 offset:34816
	ds_read_b128 v[222:225], v151 offset:35840
	ds_read_b128 v[226:229], v151 offset:36864
	ds_read_b128 v[230:233], v151 offset:37888
	ds_read_b128 v[234:237], v151 offset:38912
	ds_read_b128 v[238:241], v151 offset:39936
	s_add_u32 s100, s24, 0x40000
	s_addc_u32 s101, s25, 0
	global_load_lds_dwordx4 v0, s[100:101]
	s_add_i32 m0, s2, 0x16000
	s_nop 0
	global_load_lds_dwordx4 v130, s[100:101]
	s_mov_b32 m0, s34
	s_nop 0
	global_load_lds_dwordx4 v134, s[26:27]
	s_mov_b32 m0, s35
	s_nop 0
	global_load_lds_dwordx4 v132, s[26:27]
	s_waitcnt vmcnt(8)
	s_waitcnt lgkmcnt(0)
	s_barrier
	s_setprio 1
	s_waitcnt lgkmcnt(0)
	v_mfma_f32_16x16x32_bf16 v[126:129], v[142:145], v[196:199], v[126:129]
	v_mfma_f32_16x16x32_bf16 v[118:121], v[172:175], v[196:199], v[118:121]
	v_mfma_f32_16x16x32_bf16 v[110:113], v[142:145], v[218:221], v[110:113]
	v_mfma_f32_16x16x32_bf16 v[102:105], v[172:175], v[218:221], v[102:105]
	v_mfma_f32_16x16x32_bf16 v[94:97], v[142:145], v[226:229], v[94:97]
	v_mfma_f32_16x16x32_bf16 v[86:89], v[172:175], v[226:229], v[86:89]
	v_mfma_f32_16x16x32_bf16 v[78:81], v[142:145], v[234:237], v[78:81]
	v_mfma_f32_16x16x32_bf16 v[70:73], v[172:175], v[234:237], v[70:73]
	v_mfma_f32_16x16x32_bf16 v[126:129], v[152:155], v[214:217], v[126:129]
	v_mfma_f32_16x16x32_bf16 v[118:121], v[176:179], v[214:217], v[118:121]
	v_mfma_f32_16x16x32_bf16 v[110:113], v[152:155], v[222:225], v[110:113]
	v_mfma_f32_16x16x32_bf16 v[102:105], v[176:179], v[222:225], v[102:105]
	v_mfma_f32_16x16x32_bf16 v[94:97], v[152:155], v[230:233], v[94:97]
	v_mfma_f32_16x16x32_bf16 v[86:89], v[176:179], v[230:233], v[86:89]
	v_mfma_f32_16x16x32_bf16 v[78:81], v[152:155], v[238:241], v[78:81]
	v_mfma_f32_16x16x32_bf16 v[70:73], v[176:179], v[238:241], v[70:73]
	s_setprio 0
	s_setprio 1
	v_mfma_f32_16x16x32_bf16 v[122:125], v[180:183], v[196:199], v[122:125]
	v_mfma_f32_16x16x32_bf16 v[114:117], v[188:191], v[196:199], v[114:117]
	v_mfma_f32_16x16x32_bf16 v[106:109], v[180:183], v[218:221], v[106:109]
	v_mfma_f32_16x16x32_bf16 v[98:101], v[188:191], v[218:221], v[98:101]
	v_mfma_f32_16x16x32_bf16 v[90:93], v[180:183], v[226:229], v[90:93]
	v_mfma_f32_16x16x32_bf16 v[82:85], v[188:191], v[226:229], v[82:85]
	v_mfma_f32_16x16x32_bf16 v[74:77], v[180:183], v[234:237], v[74:77]
	v_mfma_f32_16x16x32_bf16 v[66:69], v[188:191], v[234:237], v[66:69]
	v_mfma_f32_16x16x32_bf16 v[122:125], v[184:187], v[214:217], v[122:125]
	v_mfma_f32_16x16x32_bf16 v[114:117], v[192:195], v[214:217], v[114:117]
	v_mfma_f32_16x16x32_bf16 v[106:109], v[184:187], v[222:225], v[106:109]
	v_mfma_f32_16x16x32_bf16 v[98:101], v[192:195], v[222:225], v[98:101]
	v_mfma_f32_16x16x32_bf16 v[90:93], v[184:187], v[230:233], v[90:93]
	v_mfma_f32_16x16x32_bf16 v[82:85], v[192:195], v[230:233], v[82:85]
	v_mfma_f32_16x16x32_bf16 v[74:77], v[184:187], v[238:241], v[74:77]
	v_mfma_f32_16x16x32_bf16 v[66:69], v[192:195], v[238:241], v[66:69]
	s_setprio 0
	s_barrier
	s_add_u32 s98, s26, 0xfffc0080
	s_addc_u32 s99, s27, -1
	s_add_i32 s26, s51, s2
	s_add_u32 s100, s24, 0x80
	s_addc_u32 s101, s25, 0
	s_mov_b32 m0, s26
	ds_read_b128 v[196:199], v151 offset:49152
	ds_read_b128 v[214:217], v151 offset:50176
	ds_read_b128 v[218:221], v151 offset:51200
	ds_read_b128 v[222:225], v151 offset:52224
	ds_read_b128 v[226:229], v151 offset:53248
	ds_read_b128 v[230:233], v151 offset:54272
	ds_read_b128 v[234:237], v151 offset:55296
	ds_read_b128 v[238:241], v151 offset:56320
	global_load_lds_dwordx4 v0, s[100:101]
	s_add_i32 m0, s26, 0x2000
	s_nop 0
	global_load_lds_dwordx4 v130, s[100:101]
	s_mov_b32 m0, s37
	s_nop 0
	global_load_lds_dwordx4 v134, s[98:99]
	s_mov_b32 m0, s38
	s_nop 0
	global_load_lds_dwordx4 v132, s[98:99]
	s_waitcnt vmcnt(6)
	s_waitcnt lgkmcnt(0)
	s_barrier
; #define PG8_WAIT_V(n) asm volatile("s_waitcnt vmcnt(" #n ")" ::: "memory")
; template <class Epi, class Sched, bool ALIGN_EPI = false, bool SP2 = false>
; __device__ __forceinline__ void gemm_phase(PG8_LAS unsigned char* lds, const Gemm g, const Sched& S, const Epi& E) {
;     ...
;             PG8_WAIT_V(8); PG8_WAIT_L(0); PG8_BAR; PG8_MMA(1, 0, At, B0); PG8_MMA(1, 1, At, B1); PG8_BAR; PG8_SCHED;
;             } else {
;             PG8_LDB(B0, 0, 0); PG8_SCHED; PG8_LDA(At, 0, 0); PG8_STAGE(PG8_SA(1, 1), a1 + hstep, voffA);
;             PG8_WAIT_L(8); PG8_BAR; PG8_WAIT_L(0); PG8_MMA(0, 0, At, B0); PG8_BAR; PG8_SCHED;
;             PG8_LDB(B1, 0, 1); PG8_STAGE(PG8_SB(0, 0), b2, voffB);
;             PG8_BAR; PG8_WAIT_L(0); PG8_MMA(0, 1, At, B1); PG8_BAR;
;             PG8_LDA(At, 0, 1); PG8_STAGE(PG8_SA(0, 0), a2, voffA);
;             PG8_BAR; PG8_WAIT_L(0); PG8_MMA(1, 0, At, B0); PG8_BAR; PG8_SCHED;
;             PG8_STAGE(PG8_SB(0, 1), b2 + hstep, voffB);
;             PG8_WAIT_V(6); PG8_BAR; PG8_MMA(1, 1, At, B1); PG8_BAR;
;             PG8_LDB(B0, 1, 0); PG8_SCHED; PG8_LDA(At, 1, 0); PG8_STAGE(PG8_SA(0, 1), a2 + hstep, voffA);
;             PG8_WAIT_L(8); PG8_BAR; PG8_WAIT_L(0); PG8_MMA(0, 0, At, B0); PG8_BAR; PG8_SCHED;
;             PG8_LDB(B1, 1, 1); PG8_STAGE(PG8_SB(1, 0), b3, voffB);
;             PG8_BAR; PG8_WAIT_L(0); PG8_MMA(0, 1, At, B1); PG8_BAR;
;             PG8_LDA(At, 1, 1); PG8_STAGE(PG8_SA(1, 0), a3, voffA);
;             PG8_BAR; PG8_WAIT_L(0); PG8_MMA(1, 0, At, B0); PG8_BAR; PG8_SCHED;
;             PG8_STAGE(PG8_SB(1, 1), b3 + hstep, voffB);
;             PG8_WAIT_V(6); PG8_BAR; PG8_MMA(1, 1, At, B1); PG8_BAR;
;             }
;         }
;         if constexpr (ALIGN_EPI) { if (wr == 0) PG8_BAR; }
; __device__ __forceinline__ float row_rstd(const float* rsp, int row, int fq) {
;     const f32x4 v = *(const f32x4*)(rsp + (size_t)row * 16 + 4 * fq);
;     float s = (v[0] + v[1]) + (v[2] + v[3]); s += __shfl_xor(s, 16); s += __shfl_xor(s, 32);
;     return rsqrtf(s * (1.0f / 1024.0f) + RMS_EPS);
; }
;     __device__ __forceinline__ void operator()(const f32x4 (&acc)[2][2][4][2], const Unit& u, int wr, int wc, int fr, int fq) const {
;         const int row0 = u.pm * BM + wr * 64 + fr, col0 = u.pn * HALF + wc * 32 + 8 * fq;
; #pragma unroll
;         for (int ai = 0; ai < 2; ++ai)
; #pragma unroll
;             for (int m = 0; m < 4; ++m) {
	s_setprio 1
	s_waitcnt lgkmcnt(0)
	v_mfma_f32_16x16x32_bf16 v[62:65], v[142:145], v[196:199], v[62:65]
	v_mfma_f32_16x16x32_bf16 v[54:57], v[172:175], v[196:199], v[54:57]
	v_mfma_f32_16x16x32_bf16 v[46:49], v[142:145], v[218:221], v[46:49]
	v_mfma_f32_16x16x32_bf16 v[38:41], v[172:175], v[218:221], v[38:41]
	v_mfma_f32_16x16x32_bf16 v[30:33], v[142:145], v[226:229], v[30:33]
	v_mfma_f32_16x16x32_bf16 v[22:25], v[172:175], v[226:229], v[22:25]
	v_mfma_f32_16x16x32_bf16 v[14:17], v[142:145], v[234:237], v[14:17]
	v_mfma_f32_16x16x32_bf16 v[6:9], v[172:175], v[234:237], v[6:9]
	v_mfma_f32_16x16x32_bf16 v[62:65], v[152:155], v[214:217], v[62:65]
	v_mfma_f32_16x16x32_bf16 v[54:57], v[176:179], v[214:217], v[54:57]
	v_mfma_f32_16x16x32_bf16 v[46:49], v[152:155], v[222:225], v[46:49]
	v_mfma_f32_16x16x32_bf16 v[38:41], v[176:179], v[222:225], v[38:41]
	v_mfma_f32_16x16x32_bf16 v[30:33], v[152:155], v[230:233], v[30:33]
	v_mfma_f32_16x16x32_bf16 v[22:25], v[176:179], v[230:233], v[22:25]
	v_mfma_f32_16x16x32_bf16 v[14:17], v[152:155], v[238:241], v[14:17]
	v_mfma_f32_16x16x32_bf16 v[6:9], v[176:179], v[238:241], v[6:9]
	s_setprio 0
	s_setprio 1
	v_mfma_f32_16x16x32_bf16 v[58:61], v[180:183], v[196:199], v[58:61]
	v_mfma_f32_16x16x32_bf16 v[50:53], v[188:191], v[196:199], v[50:53]
	v_mfma_f32_16x16x32_bf16 v[42:45], v[180:183], v[218:221], v[42:45]
	v_mfma_f32_16x16x32_bf16 v[34:37], v[188:191], v[218:221], v[34:37]
	v_mfma_f32_16x16x32_bf16 v[26:29], v[180:183], v[226:229], v[26:29]
	v_mfma_f32_16x16x32_bf16 v[18:21], v[188:191], v[226:229], v[18:21]
	v_mfma_f32_16x16x32_bf16 v[10:13], v[180:183], v[234:237], v[10:13]
	v_mfma_f32_16x16x32_bf16 v[2:5], v[188:191], v[234:237], v[2:5]
	v_mfma_f32_16x16x32_bf16 v[58:61], v[184:187], v[214:217], v[58:61]
	v_mfma_f32_16x16x32_bf16 v[50:53], v[192:195], v[214:217], v[50:53]
	v_mfma_f32_16x16x32_bf16 v[42:45], v[184:187], v[222:225], v[42:45]
	v_mfma_f32_16x16x32_bf16 v[34:37], v[192:195], v[222:225], v[34:37]
	v_mfma_f32_16x16x32_bf16 v[26:29], v[184:187], v[230:233], v[26:29]
	v_mfma_f32_16x16x32_bf16 v[18:21], v[192:195], v[230:233], v[18:21]
	v_mfma_f32_16x16x32_bf16 v[10:13], v[184:187], v[238:241], v[10:13]
	v_mfma_f32_16x16x32_bf16 v[2:5], v[192:195], v[238:241], v[2:5]
	s_setprio 0
	s_barrier
	s_add_i32 s50, s50, 2
	s_add_u32 s22, s22, 0x100
	s_addc_u32 s23, s23, 0
	s_add_u32 s48, s48, 0x100
	s_addc_u32 s49, s49, 0
	s_cmp_gt_u32 s50, 13
	s_cbranch_scc0 .LBB0_493
	v_lshl_add_u32 v142, s45, 8, v148
	v_mov_b32_e32 v143, 0
	s_mov_b32 s26, 0x2000
	s_mov_b32 s27, 0
	v_lshlrev_b64 v[146:147], 6, v[142:143]
	v_lshl_add_u64 v[146:147], v[136:137], 0, v[146:147]
	v_lshl_add_u64 v[156:157], v[146:147], 0, s[26:27]
	global_load_dwordx4 v[172:175], v[146:147], off
	global_load_dwordx4 v[176:179], v[146:147], off offset:1024
	global_load_dwordx4 v[180:183], v[146:147], off offset:2048
	global_load_dwordx4 v[184:187], v[146:147], off offset:3072
	global_load_dwordx4 v[188:191], v[156:157], off
	global_load_dwordx4 v[192:195], v[156:157], off offset:1024
	global_load_dwordx4 v[196:199], v[156:157], off offset:2048
	global_load_dwordx4 v[214:217], v[156:157], off offset:3072
	v_xor_b32_e32 v152, 16, v201
	v_xor_b32_e32 v153, 32, v201
	v_lshlrev_b32_e32 v152, 2, v152
	v_lshlrev_b32_e32 v153, 2, v153
	v_lshl_or_b32 v144, s44, 7, v150
	v_mov_b32_e32 v145, 0
	v_mov_b32_e32 v238, s0
	v_mov_b32_e32 v239, s1
	v_mad_i64_i32 v[236:237], s[22:23], v142, s93, v[238:239]
	v_lshlrev_b64 v[240:241], 1, v[144:145]
	v_mov_b32_e32 v234, 1.0
	v_mov_b32_e32 v235, 1.0
	v_lshl_add_u64 v[236:237], v[236:237], 0, v[240:241]
	s_mov_b32 s26, 0x16000
	s_mov_b32 s24, 0x6e000
	s_mov_b32 s25, 0
	s_and_b64 vcc, exec, s[12:13]
	s_cbranch_vccz .LBB0_496
	s_barrier
